# hand-written attention loop pinned with .p2align 6 + 4 bytes (best of 12 placement phases scanned with the prompt-attention probe), pop prefetch kept
# speedup vs baseline: 1.0008x; 1.0008x over previous
; #define LAS __attribute__((address_space(3)))
; __device__ __forceinline__ int v_rd_base(int lane) { return ((lane & 3) << 3) | (((lane >> 2) & 3) << 6) | (((lane >> 4) & 1) << 5) | (((lane >> 5) & 1) << 8); }
; __device__ __forceinline__ float rowmax32(const f32x16& p0, const f32x16& p1) {
;   float pmax = p0[0];
; #pragma unroll
;   for (int r = 1; r < 16; ++r) pmax = fmaxf(pmax, p0[r]);
; #pragma unroll
;   for (int r = 0; r < 16; ++r) pmax = fmaxf(pmax, p1[r]);
;   auto rr = __builtin_amdgcn_permlane32_swap(__float_as_uint(pmax), __float_as_uint(pmax), false, false);
;   return fmaxf(__uint_as_float(rr[0]), __uint_as_float(rr[1]));
; }
; template <bool SAFE>
; __device__ __forceinline__ bool attn_unit_prompt_t(LAS unsigned char* lds, const bf16* Kg, const bf16* Vg, const bf16* Qrow0, bf16* Orow0, int NT, int qpos0, int h, const float* gnorm) {
;     ...
;   const LAS char* vrd = V_lds + v_rd_base(lane);
;     ...
;   const short one_ = (((lane >> 4) & 1) == (lane & 1)) ? (short)16256 : (short)0;
;   const bf16x8 ones = {one_, one_, one_, one_, one_, one_, one_, one_};
;   f32x16 pA0, pA1, pB0, pB1; float alA = 1.f, alB = 1.f, rmx;
;   int s0 = 2 * SHM_K, s1 = 0, s2 = SHM_K;
.LBB0_531:
	v_lshlrev_b32_e32 v37, 3, v190
	v_lshlrev_b32_e32 v39, 4, v190
	v_and_b32_e32 v38, 24, v37
	v_and_b32_e32 v39, 0xc0, v39
	v_lshlrev_b32_e32 v40, 1, v190
	v_and_b32_e32 v40, 32, v40
	v_and_b32_e32 v37, 0x100, v37
	v_add3_u32 v38, 0, v38, v39
	s_and_b32 s6, s22, 0x3fffffc0
	v_add3_u32 v194, v38, v40, v37
	v_and_b32_e32 v36, 1, v36
	v_and_b32_e32 v37, 1, v3
	s_lshl_b32 s6, s6, 2
	v_cmp_eq_u32_e32 vcc, v36, v37
	s_add_i32 s27, s6, 0
	s_mov_b32 s6, 0x5040100
	v_cndmask_b32_e32 v36, 0, v242, vcc
	v_perm_b32 v162, v36, v36, s6
	v_max_f32_e32 v36, v21, v21
	v_max_f32_e32 v38, v20, v20
	v_max_f32_e32 v36, v38, v36
	v_max3_f32 v36, v36, v22, v23
	v_max3_f32 v36, v36, v24, v25
	v_max3_f32 v36, v36, v26, v27
	v_max3_f32 v36, v36, v28, v29
	v_max3_f32 v36, v36, v30, v31
	v_max3_f32 v36, v36, v32, v33
	v_max3_f32 v36, v36, v34, v35
	v_max3_f32 v36, v36, v4, v5
	v_max3_f32 v36, v36, v6, v7
	v_max3_f32 v36, v36, v8, v9
	v_max3_f32 v36, v36, v10, v11
	v_max3_f32 v36, v36, v12, v13
	v_max3_f32 v36, v36, v14, v15
	v_max3_f32 v36, v36, v16, v17
	v_max3_f32 v36, v36, v18, v19
	v_mov_b32_e32 v38, v36
	s_nop 1
	v_permlane32_swap_b32_e32 v36, v38
	v_max_f32_e32 v38, v38, v38
	v_max_f32_e32 v36, v36, v36
	v_max_f32_e32 v36, v36, v38
	v_add_f32_e32 v213, 0, v36
	v_sub_f32_e32 v20, v20, v213
	v_sub_f32_e32 v21, v21, v213
	v_sub_f32_e32 v22, v22, v213
	v_sub_f32_e32 v23, v23, v213
	v_sub_f32_e32 v24, v24, v213
	v_sub_f32_e32 v25, v25, v213
	v_sub_f32_e32 v26, v26, v213
	v_sub_f32_e32 v27, v27, v213
	v_sub_f32_e32 v28, v28, v213
	v_sub_f32_e32 v29, v29, v213
	v_sub_f32_e32 v30, v30, v213
	v_sub_f32_e32 v31, v31, v213
	v_sub_f32_e32 v32, v32, v213
	v_sub_f32_e32 v33, v33, v213
	v_sub_f32_e32 v34, v34, v213
	v_sub_f32_e32 v35, v35, v213
	v_exp_f32_e32 v186, v20
	v_exp_f32_e32 v187, v21
	v_exp_f32_e32 v188, v22
	v_exp_f32_e32 v189, v23
	v_exp_f32_e32 v246, v24
	v_exp_f32_e32 v247, v25
	v_exp_f32_e32 v248, v26
	v_exp_f32_e32 v249, v27
	v_exp_f32_e32 v150, v28
	v_exp_f32_e32 v151, v29
	v_exp_f32_e32 v152, v30
	v_exp_f32_e32 v153, v31
	v_exp_f32_e32 v154, v32
	v_exp_f32_e32 v156, v33
	v_exp_f32_e32 v155, v34
	v_exp_f32_e32 v157, v35
	s_lshl_b32 s19, s11, 1
	s_add_i32 s27, s27, 0x1c000
	v_sub_f32_e32 v82, 0, v213
	v_sub_f32_e32 v98, v4, v213
	v_max_f32_e32 v4, v36, v36
	v_and_b32_e32 v193, 48, v3
	s_mov_b32 s35, 1
	v_mov_b32_e32 v163, v162
	v_mov_b32_e32 v164, v162
	v_mov_b32_e32 v165, v162
	v_mov_b32_e32 v83, v82
	v_mov_b32_e32 v84, v82
	v_mov_b32_e32 v85, v82
	v_mov_b32_e32 v86, v82
	v_mov_b32_e32 v87, v82
	v_mov_b32_e32 v88, v82
	v_mov_b32_e32 v89, v82
	v_mov_b32_e32 v90, v82
	v_mov_b32_e32 v91, v82
	v_mov_b32_e32 v92, v82
	v_mov_b32_e32 v93, v82
	v_mov_b32_e32 v94, v82
	v_mov_b32_e32 v95, v82
	v_mov_b32_e32 v96, v82
	v_mov_b32_e32 v97, v82
	v_sub_f32_e32 v113, v19, v213
	v_sub_f32_e32 v112, v18, v213
	v_sub_f32_e32 v111, v17, v213
	v_sub_f32_e32 v110, v16, v213
	v_sub_f32_e32 v109, v15, v213
	v_sub_f32_e32 v108, v14, v213
	v_sub_f32_e32 v107, v13, v213
	v_sub_f32_e32 v106, v12, v213
	v_sub_f32_e32 v105, v11, v213
	v_sub_f32_e32 v104, v10, v213
	v_sub_f32_e32 v103, v9, v213
	v_sub_f32_e32 v102, v8, v213
	v_sub_f32_e32 v101, v7, v213
	v_sub_f32_e32 v100, v6, v213
	v_sub_f32_e32 v99, v5, v213
	s_cmpk_gt_u32 s10, 0x1f3
	v_cmp_gt_u32_e64 s[6:7], 32, v190
	v_lshlrev_b32_e32 v195, 6, v37
	v_lshl_or_b32 v8, s24, 7, v196
	v_max_f32_e32 v210, 0, v4
	v_add_u32_e32 v223, s27, v193
	s_cbranch_scc1 .LBB0_547
	s_add_i32 s20, s19, -3
	v_or_b32_e32 v4, 32, v8
	v_xad_u32 v10, v4, v146, v218
	v_or_b32_e32 v4, 64, v8
	s_cmp_lg_u32 s28, 0
	v_mov_b32_e32 v66, v197
	v_mov_b32_e32 v67, v197
	v_xad_u32 v11, v4, v146, v218
	v_or_b32_e32 v4, 0x60, v8
	s_cselect_b64 s[10:11], -1, 0
	s_add_u32 s21, s16, s92
	v_mov_b32_e32 v68, v197
	v_mov_b32_e32 v69, v197
	v_mov_b32_e32 v70, v197
	v_mov_b32_e32 v71, v197
	v_mov_b32_e32 v72, v197
	v_mov_b32_e32 v73, v197
	v_mov_b32_e32 v74, v197
	v_mov_b32_e32 v75, v197
	v_mov_b32_e32 v76, v197
	v_mov_b32_e32 v77, v197
	v_mov_b32_e32 v78, v197
	v_mov_b32_e32 v79, v197
	v_mov_b32_e32 v80, v197
	v_mov_b32_e32 v81, v197
	v_mov_b64_e32 v[50:51], v[66:67]
	v_mov_b64_e32 v[34:35], v[66:67]
	v_mov_b64_e32 v[18:19], v[66:67]
	v_xad_u32 v9, v8, v146, v218
	v_xad_u32 v12, v4, v146, v218
	s_mov_b32 s8, 0
	v_lshl_add_u32 v13, v192, 2, s27
	s_addc_u32 s34, s17, 0
	v_mov_b32_e32 v182, v197
	v_mov_b32_e32 v183, v197
	v_mov_b32_e32 v184, v197
	v_mov_b32_e32 v185, v197
	s_mov_b32 s65, 0x8000
	s_movk_i32 s64, 0x4000
	s_mov_b32 s36, 0x10000
	s_mov_b64 s[12:13], 0
	v_mov_b64_e32 v[52:53], v[68:69]
	v_mov_b64_e32 v[54:55], v[70:71]
	v_mov_b64_e32 v[56:57], v[72:73]
	v_mov_b64_e32 v[58:59], v[74:75]
	v_mov_b64_e32 v[60:61], v[76:77]
	v_mov_b64_e32 v[62:63], v[78:79]
	v_mov_b64_e32 v[64:65], v[80:81]
	v_mov_b64_e32 v[36:37], v[68:69]
	v_mov_b64_e32 v[38:39], v[70:71]
	v_mov_b64_e32 v[40:41], v[72:73]
	v_mov_b64_e32 v[42:43], v[74:75]
	v_mov_b64_e32 v[44:45], v[76:77]
	v_mov_b64_e32 v[46:47], v[78:79]
	v_mov_b64_e32 v[48:49], v[80:81]
	v_mov_b64_e32 v[20:21], v[68:69]
	v_mov_b64_e32 v[22:23], v[70:71]
	v_mov_b64_e32 v[24:25], v[72:73]
	v_mov_b64_e32 v[26:27], v[74:75]
	v_mov_b64_e32 v[28:29], v[76:77]
	v_mov_b64_e32 v[30:31], v[78:79]
	v_mov_b64_e32 v[32:33], v[80:81]
	v_cvt_pk_bf16_f32 v130, v186, v187
	v_cvt_pk_bf16_f32 v131, v188, v189
	v_cvt_pk_bf16_f32 v132, v246, v247
	v_cvt_pk_bf16_f32 v133, v248, v249
	v_cvt_pk_bf16_f32 v134, v150, v151
	v_cvt_pk_bf16_f32 v135, v152, v153
	v_cvt_pk_bf16_f32 v136, v154, v156
	v_cvt_pk_bf16_f32 v137, v155, v157
	s_and_b32 s66, s36, 0xc000
	v_add_u32_e32 v147, s66, v194
	ds_read_b64_tr_b16 v[246:247], v147 offset:49152
	ds_read_b64_tr_b16 v[248:249], v147 offset:51200
	ds_read_b64_tr_b16 v[250:251], v147 offset:49664
	ds_read_b64_tr_b16 v[252:253], v147 offset:51712
	ds_read_b64_tr_b16 v[198:199], v147 offset:50176
	ds_read_b64_tr_b16 v[200:201], v147 offset:52224
	ds_read_b64_tr_b16 v[202:203], v147 offset:50688
	ds_read_b64_tr_b16 v[204:205], v147 offset:52736
	ds_read_b64_tr_b16 v[206:207], v147 offset:53248
	ds_read_b64_tr_b16 v[208:209], v147 offset:55296
	ds_read_b64_tr_b16 v[236:237], v147 offset:53760
	ds_read_b64_tr_b16 v[238:239], v147 offset:55808
	ds_read_b64_tr_b16 v[240:241], v147 offset:54272
	ds_read_b64_tr_b16 v[242:243], v147 offset:56320
	ds_read_b64_tr_b16 v[232:233], v147 offset:54784
	ds_read_b64_tr_b16 v[234:235], v147 offset:56832
	.p2align 6
	s_nop 0
